# dropped the second prologue barrier of each attention unit (tile 1 is already published by the first one after the prologue DMA de-serialisation; its lgkmcnt wait stays)
# speedup vs baseline: 1.0091x; 1.0091x over previous
; __device__ __forceinline__ void attn_dense_body(const bf16* Qb, const bf16* __restrict__ Kh, const bf16* __restrict__ Vh, const bf16* __restrict__ Zb, ...
;     ...
;   const TQ* Qw = Qb + (long)(wid * QBLK + r32) * LDQ + hi * 8;
; #pragma unroll
;   for (int d0 = 0; d0 < 8; ++d0) qr[d0] = SQ::tobf(SQ::ld8(Qw + d0 * 16));
;   float negBC;
;   { float ss = 0.f;
; #pragma unroll
;     for (int d0 = 0; d0 < 8; ++d0)
; #pragma unroll
;       for (int e = 0; e < 8; ++e) { const float qv = __uint_as_float((unsigned)(unsigned short)qr[d0][e] << 16); ss = fmaf(qv, qv, ss); }
;     auto rr = __builtin_amdgcn_permlane32_swap(__float_as_uint(ss), __float_as_uint(ss), false, false);
;     ss = __uint_as_float(rr[0]) + __uint_as_float(rr[1]);
;     negBC = -(sqrtf(ss) * kmax * (11.313708498984761f * 1.01f) + 0.07f); }
; __global__ void __launch_bounds__(NTHREADS, 2) mega(Params P) {
;     ...
;                 if (un < 1024) { b = un >> 9; h = (un >> 6) & 7; rowq = b * TB + CTXL + (un & 63) * 256; seq = TB; }
;                 else { const int c = un - 1024; b = c >> 3; h = c & 7; rowq = b * TB; seq = CTXL; }
;                 const size_t qoff = (size_t)rowq * DM + h * 128, koff = (size_t)b * TB * 256 + (h >> 2) * 128;
;                 att::attn_dense_body((const att::bf16*)(Q + qoff), (const att::bf16*)(Kb + koff), (const att::bf16*)(Vb + koff), (const att::bf16*)(ZA + qoff), (att::bf16*)(Q + qoff), seq, (char*)lds, wave, kmax, l3);
.LBB0_116:
	s_and_b32 s16, s15, 7
	s_ashr_i32 s25, s24, 31
	s_lshl_b64 s[24:25], s[24:25], 10
	s_lshl_b32 s16, s16, 7
	s_lshl_b32 s17, s15, 5
	s_or_b32 s24, s24, s16
	s_mul_i32 s16, s14, 0x410000
	s_and_b32 s17, s17, 0x80
	v_mov_b32_e32 v32, v236
	s_or_b32 s40, s16, s17
	s_lshl_b64 s[44:45], s[24:25], 1
	s_add_u32 s24, s8, s44
	v_and_b32_e32 v10, 31, v32
	v_ashrrev_i32_e32 v245, 5, v32
	v_or_b32_e32 v160, s69, v10
	s_addc_u32 s25, s9, s45
	v_lshlrev_b64 v[0:1], 11, v[160:161]
	v_lshlrev_b32_e32 v2, 3, v245
	v_lshl_add_u64 v[0:1], s[24:25], 0, v[0:1]
	v_ashrrev_i32_e32 v3, 31, v2
	v_lshl_add_u64 v[0:1], v[2:3], 1, v[0:1]
	flat_load_dwordx4 v[140:143], v[0:1]
	flat_load_dwordx4 v[136:139], v[0:1] offset:32
	flat_load_dwordx4 v[132:135], v[0:1] offset:64
	flat_load_dwordx4 v[128:131], v[0:1] offset:96
	flat_load_dwordx4 v[124:127], v[0:1] offset:128
	flat_load_dwordx4 v[120:123], v[0:1] offset:160
	flat_load_dwordx4 v[116:119], v[0:1] offset:192
	flat_load_dwordx4 v[112:115], v[0:1] offset:224
	s_mov_b32 s16, 0xf800000
	s_mul_hi_i32 s41, s14, 0x410000
	s_lshl_b64 s[40:41], s[40:41], 1
	s_add_u32 s46, s10, s40
	s_addc_u32 s47, s11, s41
	s_add_u32 s48, s12, s40
	s_addc_u32 s49, s13, s41
	s_add_i32 m0, s90, 0xc000
	v_mov_b32_e32 v146, 0
	s_mov_b32 s54, 0
	v_mov_b32_e32 v58, v146
	v_mov_b32_e32 v59, v146
	v_mov_b32_e32 v60, v146
	v_mov_b32_e32 v61, v146
	v_mov_b32_e32 v62, v146
	v_mov_b32_e32 v63, v146
	s_waitcnt vmcnt(0) lgkmcnt(0)
	v_lshlrev_b32_e32 v0, 16, v140
	v_and_b32_e32 v1, 0xffff0000, v140
	v_fma_f32 v0, v0, v0, 0
	v_lshlrev_b32_e32 v2, 16, v141
	v_fmac_f32_e32 v0, v1, v1
	v_and_b32_e32 v3, 0xffff0000, v141
	v_fmac_f32_e32 v0, v2, v2
	v_lshlrev_b32_e32 v4, 16, v142
	v_fmac_f32_e32 v0, v3, v3
	v_and_b32_e32 v5, 0xffff0000, v142
	v_fmac_f32_e32 v0, v4, v4
	v_lshlrev_b32_e32 v6, 16, v143
	v_fmac_f32_e32 v0, v5, v5
	v_and_b32_e32 v7, 0xffff0000, v143
	v_fmac_f32_e32 v0, v6, v6
	v_lshlrev_b32_e32 v8, 16, v136
	v_fmac_f32_e32 v0, v7, v7
	v_and_b32_e32 v9, 0xffff0000, v136
	v_fmac_f32_e32 v0, v8, v8
	v_lshlrev_b32_e32 v11, 16, v137
	v_fmac_f32_e32 v0, v9, v9
	v_and_b32_e32 v12, 0xffff0000, v137
	v_fmac_f32_e32 v0, v11, v11
	v_lshlrev_b32_e32 v13, 16, v138
	v_fmac_f32_e32 v0, v12, v12
	v_and_b32_e32 v14, 0xffff0000, v138
	v_fmac_f32_e32 v0, v13, v13
	v_lshlrev_b32_e32 v15, 16, v139
	v_fmac_f32_e32 v0, v14, v14
	v_and_b32_e32 v16, 0xffff0000, v139
	v_fmac_f32_e32 v0, v15, v15
	v_lshlrev_b32_e32 v17, 16, v132
	v_fmac_f32_e32 v0, v16, v16
	v_and_b32_e32 v18, 0xffff0000, v132
	v_fmac_f32_e32 v0, v17, v17
	v_lshlrev_b32_e32 v19, 16, v133
	v_fmac_f32_e32 v0, v18, v18
	v_and_b32_e32 v20, 0xffff0000, v133
	v_fmac_f32_e32 v0, v19, v19
	v_lshlrev_b32_e32 v21, 16, v134
	v_fmac_f32_e32 v0, v20, v20
	v_and_b32_e32 v22, 0xffff0000, v134
	v_fmac_f32_e32 v0, v21, v21
	v_lshlrev_b32_e32 v23, 16, v135
	v_fmac_f32_e32 v0, v22, v22
	v_and_b32_e32 v24, 0xffff0000, v135
	v_fmac_f32_e32 v0, v23, v23
	v_lshlrev_b32_e32 v25, 16, v128
	v_fmac_f32_e32 v0, v24, v24
	v_and_b32_e32 v26, 0xffff0000, v128
	v_fmac_f32_e32 v0, v25, v25
	v_lshlrev_b32_e32 v27, 16, v129
	v_fmac_f32_e32 v0, v26, v26
	v_and_b32_e32 v28, 0xffff0000, v129
	v_fmac_f32_e32 v0, v27, v27
	v_lshlrev_b32_e32 v29, 16, v130
	v_fmac_f32_e32 v0, v28, v28
	v_and_b32_e32 v30, 0xffff0000, v130
	v_fmac_f32_e32 v0, v29, v29
	v_lshlrev_b32_e32 v31, 16, v131
	v_fmac_f32_e32 v0, v30, v30
	v_and_b32_e32 v33, 0xffff0000, v131
	v_fmac_f32_e32 v0, v31, v31
	v_lshlrev_b32_e32 v34, 16, v124
	v_fmac_f32_e32 v0, v33, v33
	v_and_b32_e32 v35, 0xffff0000, v124
	v_fmac_f32_e32 v0, v34, v34
	v_lshlrev_b32_e32 v36, 16, v125
	v_fmac_f32_e32 v0, v35, v35
	v_and_b32_e32 v37, 0xffff0000, v125
	v_fmac_f32_e32 v0, v36, v36
	v_lshlrev_b32_e32 v38, 16, v126
	v_fmac_f32_e32 v0, v37, v37
	v_and_b32_e32 v39, 0xffff0000, v126
	v_fmac_f32_e32 v0, v38, v38
	v_lshlrev_b32_e32 v40, 16, v127
	v_fmac_f32_e32 v0, v39, v39
	v_and_b32_e32 v41, 0xffff0000, v127
	v_fmac_f32_e32 v0, v40, v40
	v_lshlrev_b32_e32 v42, 16, v120
	v_fmac_f32_e32 v0, v41, v41
	v_and_b32_e32 v43, 0xffff0000, v120
	v_fmac_f32_e32 v0, v42, v42
	v_lshlrev_b32_e32 v44, 16, v121
	v_fmac_f32_e32 v0, v43, v43
	v_and_b32_e32 v45, 0xffff0000, v121
	v_fmac_f32_e32 v0, v44, v44
	v_lshlrev_b32_e32 v46, 16, v122
	v_fmac_f32_e32 v0, v45, v45
	v_and_b32_e32 v47, 0xffff0000, v122
	v_fmac_f32_e32 v0, v46, v46
	v_lshlrev_b32_e32 v48, 16, v123
	v_fmac_f32_e32 v0, v47, v47
	v_and_b32_e32 v49, 0xffff0000, v123
	v_fmac_f32_e32 v0, v48, v48
	v_lshlrev_b32_e32 v50, 16, v116
	v_fmac_f32_e32 v0, v49, v49
	v_and_b32_e32 v51, 0xffff0000, v116
	v_fmac_f32_e32 v0, v50, v50
	v_lshlrev_b32_e32 v52, 16, v117
	v_fmac_f32_e32 v0, v51, v51
	v_and_b32_e32 v53, 0xffff0000, v117
	v_fmac_f32_e32 v0, v52, v52
	v_lshlrev_b32_e32 v54, 16, v118
	v_fmac_f32_e32 v0, v53, v53
	v_and_b32_e32 v55, 0xffff0000, v118
	v_fmac_f32_e32 v0, v54, v54
	v_lshlrev_b32_e32 v56, 16, v119
	v_fmac_f32_e32 v0, v55, v55
	v_and_b32_e32 v57, 0xffff0000, v119
	v_fmac_f32_e32 v0, v56, v56
	v_fmac_f32_e32 v0, v57, v57
	v_lshlrev_b32_e32 v1, 16, v112
	v_fmac_f32_e32 v0, v1, v1
	v_and_b32_e32 v1, 0xffff0000, v112
	v_fmac_f32_e32 v0, v1, v1
	v_lshlrev_b32_e32 v1, 16, v113
	v_fmac_f32_e32 v0, v1, v1
	v_and_b32_e32 v1, 0xffff0000, v113
	v_fmac_f32_e32 v0, v1, v1
	v_lshlrev_b32_e32 v1, 16, v114
	v_fmac_f32_e32 v0, v1, v1
	v_and_b32_e32 v1, 0xffff0000, v114
	v_fmac_f32_e32 v0, v1, v1
	v_lshlrev_b32_e32 v1, 16, v115
	v_fmac_f32_e32 v0, v1, v1
	v_and_b32_e32 v1, 0xffff0000, v115
	v_fmac_f32_e32 v0, v1, v1
	v_mov_b32_e32 v1, v0
	s_nop 1
	v_permlane32_swap_b32_e32 v0, v1
	v_add_f32_e32 v0, v0, v1
	v_mul_f32_e32 v1, 0x4f800000, v0
	v_cmp_gt_f32_e32 vcc, s16, v0
; __device__ __forceinline__ int v_rd_base2(int lane) { return ((lane & 3) << 3) | (((lane >> 2) & 3) << 6) | (((lane >> 4) & 1) << 5) | (((lane >> 5) & 1) << 11); }
; #define DWAIT() asm volatile("s_waitcnt vmcnt(0)" ::: "memory")
; __device__ __forceinline__ void attn_dense_body(const bf16* Qb, const bf16* __restrict__ Kh, const bf16* __restrict__ Vh, const bf16* __restrict__ Zb, ...
;     ...
;     negBC = -(sqrtf(ss) * kmax * (11.313708498984761f * 1.01f) + 0.07f); }
;   f32x16 cinit; for (int r = 0; r < 16; ++r) cinit[r] = negBC;
;   const int vb0 = (int)(uintptr_t)V_lds + v_rd_base2(lane);
;   int koff0, koff1, voff0, voff1;
;   { const int rk0 = 8 * wid + (lane >> 4), rk1 = rk0 + 4; koff0 = rk0 * (LDK * 2) + (((lane & 15) ^ (rk0 & 15)) << 4); koff1 = rk1 * (LDK * 2) + (((lane & 15) ^ (rk1 & 15)) << 4);
;     const int st0 = 4 * wid + (lane >> 5), st1 = st0 + 2, q8 = (lane & 31) >> 2;
;     const int kk0 = ((st0 >> 2) << 3) | q8, kk1 = ((st1 >> 2) << 3) | q8;
;     const int ky0 = (kk0 & ~0xC) | ((kk0 & 4) << 1) | ((kk0 & 8) >> 1), ky1 = (kk1 & ~0xC) | ((kk1 & 4) << 1) | ((kk1 & 8) >> 1);
;     voff0 = ky0 * (LDK * 2) + ((st0 & 3) * 32 + (lane & 3) * 8) * 2; voff1 = ky1 * (LDK * 2) + ((st1 & 3) * 32 + (lane & 3) * 8) * 2; }
;     ...
;   f32x16 pA0, pA1, pB0, pB1; bf16x8 pa0, pa1, pa2, pa3; const int NT = seq / KVBLK;
;   SDMA(0, 0); DWAIT(); __syncthreads();
	v_ashrrev_i32_e32 v43, 4, v32
	v_bfe_u32 v48, v32, 2, 2
	v_cndmask_b32_e32 v0, v0, v1, vcc
	v_sqrt_f32_e32 v1, v0
	v_lshlrev_b32_e32 v42, 4, v32
	v_lshlrev_b32_e32 v52, 4, v245
	v_lshlrev_b32_e32 v53, 8, v10
	v_add_u32_e32 v2, -1, v1
	v_fma_f32 v3, -v2, v1, v0
	v_cmp_ge_f32_e64 s[40:41], 0, v3
	v_add_u32_e32 v3, 1, v1
	v_and_b32_e32 v54, 0xf0, v42
	v_cndmask_b32_e64 v2, v1, v2, s[40:41]
	v_fma_f32 v1, -v3, v1, v0
	v_cmp_lt_f32_e64 s[40:41], 0, v1
	v_xad_u32 v157, v54, v52, v53
	s_movk_i32 s16, 0xc0
	v_cndmask_b32_e64 v1, v2, v3, s[40:41]
	v_mul_f32_e32 v2, 0x37800000, v1
	v_cndmask_b32_e32 v1, v1, v2, vcc
	v_cmp_class_f32_e32 vcc, v0, v233
	v_mov_b32_e32 v55, v146
	v_mov_b32_e32 v56, v146
	v_cndmask_b32_e32 v0, v1, v0, vcc
	v_mul_f32_e32 v0, v145, v0
	v_fmamk_f32 v0, v0, 0x4136d45c, v234
	v_xor_b32_e32 v64, 0x80000000, v0
	v_lshlrev_b32_e32 v0, 3, v32
	v_and_b32_e32 v33, 24, v0
	v_add_u32_e32 v0, s88, v43
	v_xor_b32_e32 v2, v0, v32
	v_add_u32_e32 v1, 4, v0
	v_lshlrev_b32_e32 v2, 4, v2
	v_and_b32_e32 v44, 0xf0, v2
	v_xor_b32_e32 v2, v1, v32
	v_lshlrev_b32_e32 v2, 4, v2
	v_and_b32_e32 v45, 0xf0, v2
	v_lshl_or_b32 v2, v1, 9, v45
	v_add_u32_e32 v1, s89, v245
	v_add_u32_e32 v3, 2, v1
	v_lshlrev_b32_e32 v4, 1, v1
	v_and_b32_e32 v46, -16, v4
	v_lshlrev_b32_e32 v4, 1, v3
	v_and_b32_e32 v47, -16, v4
	v_lshrrev_b32_e32 v4, 1, v32
	v_and_b32_e32 v51, 4, v3
	v_and_b32_e32 v49, 8, v4
	v_and_b32_e32 v50, 4, v1
	v_or_b32_e32 v4, v51, v47
	v_or_b32_e32 v1, v50, v46
	v_or3_b32 v5, v4, v48, v49
	v_and_or_b32 v4, v32, s93, v33
	v_or3_b32 v1, v1, v48, v49
	v_lshlrev_b32_e32 v4, 1, v4
	v_lshl_or_b32 v4, v1, 9, v4
	v_lshlrev_b32_e32 v1, 5, v3
	v_and_or_b32 v1, v1, s93, v33
	v_lshl_or_b32 v0, v0, 9, v44
	v_lshlrev_b32_e32 v1, 1, v1
	v_lshl_or_b32 v6, v5, 9, v1
	v_ashrrev_i32_e32 v1, 31, v0
	v_lshl_add_u64 v[8:9], s[46:47], 0, v[0:1]
	v_ashrrev_i32_e32 v3, 31, v2
	global_load_lds_dwordx4 v[8:9], off
	v_lshl_add_u64 v[8:9], s[46:47], 0, v[2:3]
	s_add_i32 m0, s90, 0xc400
	v_ashrrev_i32_e32 v5, 31, v4
	global_load_lds_dwordx4 v[8:9], off
	v_lshl_add_u64 v[8:9], s[48:49], 0, v[4:5]
	s_mov_b32 m0, s90
	v_ashrrev_i32_e32 v7, 31, v6
	global_load_lds_dwordx4 v[8:9], off
	s_add_i32 m0, s90, 0x400
	s_add_u32 s40, s46, 0x8000
	s_addc_u32 s41, s47, 0
	v_lshl_add_u64 v[8:9], s[48:49], 0, v[6:7]
	s_add_u32 s46, s48, 0x8000
	global_load_lds_dwordx4 v[8:9], off
	s_addc_u32 s47, s49, 0
	v_lshl_add_u64 v[0:1], s[40:41], 0, v[0:1]
	s_add_i32 m0, s90, 0x10000
	s_nop 0
	global_load_lds_dwordx4 v[0:1], off
	v_lshl_add_u64 v[0:1], s[40:41], 0, v[2:3]
	s_add_i32 m0, s90, 0x10400
	s_nop 0
	global_load_lds_dwordx4 v[0:1], off
	v_lshl_add_u64 v[0:1], s[46:47], 0, v[4:5]
	s_add_i32 m0, s90, 0x4000
	s_nop 0
	global_load_lds_dwordx4 v[0:1], off
	v_lshl_add_u64 v[0:1], s[46:47], 0, v[6:7]
	s_add_i32 m0, s90, 0x4400
	s_nop 0
	global_load_lds_dwordx4 v[0:1], off
	s_waitcnt vmcnt(0)
	s_waitcnt vmcnt(0) lgkmcnt(0)
	s_barrier
; __device__ __forceinline__ void partialSM3(f32x16& p0) { for (int r = 0; r < 16; ++r) p0[r] = __builtin_amdgcn_exp2f(p0[r]); }
; #define DWAIT() asm volatile("s_waitcnt vmcnt(0)" ::: "memory")
; __device__ __forceinline__ void attn_dense_body(const bf16* Qb, const bf16* __restrict__ Kh, const bf16* __restrict__ Vh, const bf16* __restrict__ Zb, ...
;     ...
;   SDMA(0, 0); DWAIT(); __syncthreads();
;   SDMA(1, KVBLK);
;   qkt3(pA0, pA1, K_lds, qr, r32, hi, cinit); partialSM3(pA0);
;   for (int r = 0; r < 16; ++r) pA1[r] = __builtin_amdgcn_exp2f(pA1[r]);
;   DWAIT(); __syncthreads();
;   int sP = 0, sC = 1, sN = 2;
	v_mov_b32_e32 v65, v64
	v_add_u32_e32 v4, 0, v157
	v_mov_b32_e32 v66, v64
	ds_read_b128 v[0:3], v4 offset:49152
	ds_read_b128 v[34:37], v4 offset:57344
	v_mov_b32_e32 v67, v64
	v_mov_b32_e32 v68, v64
	v_mov_b32_e32 v69, v64
	v_mov_b32_e32 v70, v64
	v_mov_b32_e32 v71, v64
	v_mov_b32_e32 v72, v64
	v_mov_b32_e32 v73, v64
	v_mov_b32_e32 v74, v64
	v_mov_b32_e32 v75, v64
	v_mov_b32_e32 v76, v64
	v_mov_b32_e32 v77, v64
	v_mov_b32_e32 v78, v64
	v_mov_b32_e32 v79, v64
	s_cmp_lg_u32 0, -1
	s_mov_b32 s46, 1
	s_waitcnt lgkmcnt(0)
	v_mfma_f32_32x32x16_bf16 v[16:31], v[0:3], v[140:143], v[64:79]
	s_mov_b32 s47, 2
	s_mov_b32 s48, 2
	v_mov_b32_e32 v57, v146
	v_mfma_f32_32x32x16_bf16 v[0:15], v[34:37], v[140:143], v[64:79]
	v_add_u32_e32 v34, 32, v52
	v_xad_u32 v177, v34, v54, v53
	v_add_u32_e32 v38, 0, v177
	ds_read_b128 v[34:37], v38 offset:49152
	ds_read_b128 v[38:41], v38 offset:57344
	s_waitcnt lgkmcnt(0)
	v_mfma_f32_32x32x16_bf16 v[16:31], v[34:37], v[136:139], v[16:31]
	v_add_u32_e32 v34, 64, v52
	v_xad_u32 v175, v34, v54, v53
	v_mfma_f32_32x32x16_bf16 v[0:15], v[38:41], v[136:139], v[0:15]
	v_add_u32_e32 v38, 0, v175
	ds_read_b128 v[34:37], v38 offset:49152
	ds_read_b128 v[38:41], v38 offset:57344
	s_waitcnt lgkmcnt(0)
	v_mfma_f32_32x32x16_bf16 v[16:31], v[34:37], v[132:135], v[16:31]
	v_add_u32_e32 v34, 0x60, v52
	v_xad_u32 v173, v34, v54, v53
	v_mfma_f32_32x32x16_bf16 v[0:15], v[38:41], v[132:135], v[0:15]
	v_add_u32_e32 v38, 0, v173
	ds_read_b128 v[34:37], v38 offset:49152
	ds_read_b128 v[38:41], v38 offset:57344
	s_waitcnt lgkmcnt(0)
	v_mfma_f32_32x32x16_bf16 v[16:31], v[34:37], v[128:131], v[16:31]
	v_add_u32_e32 v34, 0x80, v52
	v_xad_u32 v171, v34, v54, v53
	v_mfma_f32_32x32x16_bf16 v[0:15], v[38:41], v[128:131], v[0:15]
	v_add_u32_e32 v38, 0, v171
	ds_read_b128 v[34:37], v38 offset:49152
	ds_read_b128 v[38:41], v38 offset:57344
	s_waitcnt lgkmcnt(0)
	v_mfma_f32_32x32x16_bf16 v[16:31], v[34:37], v[124:127], v[16:31]
	v_add_u32_e32 v34, 0xa0, v52
	v_xad_u32 v169, v34, v54, v53
	v_mfma_f32_32x32x16_bf16 v[0:15], v[38:41], v[124:127], v[0:15]
	v_add_u32_e32 v38, 0, v169
	ds_read_b128 v[34:37], v38 offset:49152
	ds_read_b128 v[38:41], v38 offset:57344
	s_waitcnt lgkmcnt(0)
	v_mfma_f32_32x32x16_bf16 v[16:31], v[34:37], v[120:123], v[16:31]
	v_add_u32_e32 v34, 0xc0, v52
	v_xad_u32 v167, v34, v54, v53
	v_mfma_f32_32x32x16_bf16 v[0:15], v[38:41], v[120:123], v[0:15]
	v_add_u32_e32 v38, 0, v167
	ds_read_b128 v[34:37], v38 offset:49152
	ds_read_b128 v[38:41], v38 offset:57344
	s_waitcnt lgkmcnt(0)
	v_mfma_f32_32x32x16_bf16 v[16:31], v[34:37], v[116:119], v[16:31]
	v_add_u32_e32 v34, 0xe0, v52
	v_xad_u32 v159, v34, v54, v53
	v_mov_b32_e32 v52, v146
	v_mov_b32_e32 v53, v146
	v_mov_b32_e32 v54, v146
	v_mfma_f32_32x32x16_bf16 v[0:15], v[38:41], v[116:119], v[0:15]
	v_add_u32_e32 v38, 0, v159
	ds_read_b128 v[34:37], v38 offset:49152
	ds_read_b128 v[38:41], v38 offset:57344
	s_waitcnt vmcnt(0)
	s_waitcnt vmcnt(0) lgkmcnt(0)
	v_mfma_f32_32x32x16_bf16 v[0:15], v[38:41], v[112:115], v[0:15]
	v_mov_b32_e32 v38, v146
	v_mov_b32_e32 v39, v146
	v_mov_b32_e32 v40, v146
	v_mov_b32_e32 v41, v146
	s_nop 7
	v_exp_f32_e32 v168, v0
	v_mfma_f32_32x32x16_bf16 v[16:31], v[34:37], v[112:115], v[16:31]
	v_exp_f32_e32 v156, v1
	v_or_b32_e32 v0, v47, v49
	v_add_u16_e32 v1, 2, v245
	v_lshlrev_b32_e32 v34, 1, v32
	v_or3_b32 v0, v0, v51, v48
	v_and_b32_e32 v1, 3, v1
	v_and_b32_e32 v35, 32, v34
	v_lshlrev_b32_e32 v32, 6, v32
	v_exp_f32_e32 v158, v2
	v_lshlrev_b32_e32 v0, 9, v0
	v_lshlrev_b32_e32 v1, 6, v1
	v_and_b32_e32 v2, 48, v42
	v_and_or_b32 v35, v42, s16, v35
	v_and_b32_e32 v32, 0x800, v32
	v_or3_b32 v148, v0, v1, v2
	v_or_b32_e32 v0, v46, v49
	v_or3_b32 v32, v35, v32, v33
	s_cselect_b32 s16, 0, 0
	s_lshl_b32 s15, s15, 6
	v_or3_b32 v0, v0, v50, v48
	v_add_u32_e32 v147, s16, v32
	v_exp_f32_e32 v179, v16
	v_exp_f32_e32 v170, v17
	v_exp_f32_e32 v172, v18
	v_exp_f32_e32 v174, v19
	v_exp_f32_e32 v184, v20
	v_exp_f32_e32 v186, v21
	v_exp_f32_e32 v188, v22
	v_exp_f32_e32 v190, v23
	v_exp_f32_e32 v206, v24
	v_exp_f32_e32 v200, v25
	v_exp_f32_e32 v202, v26
	v_exp_f32_e32 v204, v27
	v_exp_f32_e32 v216, v28
	v_exp_f32_e32 v218, v29
	v_exp_f32_e32 v220, v30
	v_exp_f32_e32 v222, v31
	v_exp_f32_e32 v166, v3
	v_exp_f32_e32 v176, v4
	v_exp_f32_e32 v178, v5
	v_exp_f32_e32 v180, v6
	v_exp_f32_e32 v182, v7
	v_exp_f32_e32 v198, v8
	v_exp_f32_e32 v196, v9
	v_exp_f32_e32 v192, v10
	v_exp_f32_e32 v194, v11
	v_exp_f32_e32 v208, v12
	v_exp_f32_e32 v210, v13
	v_exp_f32_e32 v212, v14
	v_exp_f32_e32 v214, v15
	s_mul_hi_i32 s16, s14, 0x820000
	s_mul_i32 s14, s14, 0x820000
	s_and_b32 s15, s15, 0x100
	v_lshlrev_b32_e32 v0, 9, v0
	v_and_b32_e32 v1, 0xc0, v34
	s_or_b32 s14, s14, s15
	v_or3_b32 v150, v0, v1, v2
	v_lshlrev_b32_e32 v0, 9, v43
	s_add_u32 s40, s42, s14
	v_add3_u32 v152, s92, v0, v45
	v_add3_u32 v154, s63, v0, v44
	v_ashrrev_i32_e32 v149, 31, v148
	s_addc_u32 s41, s43, s16
	v_ashrrev_i32_e32 v151, 31, v150
	v_ashrrev_i32_e32 v153, 31, v152
	v_ashrrev_i32_e32 v155, 31, v154
	v_mov_b32_e32 v0, 0
	v_mov_b32_e32 v1, v146
	v_mov_b32_e32 v2, v146
	v_mov_b32_e32 v3, v146
	v_mov_b32_e32 v4, v146
	v_mov_b32_e32 v5, v146
	v_mov_b32_e32 v6, v146
	v_mov_b32_e32 v7, v146
	v_mov_b32_e32 v8, v146
	v_mov_b32_e32 v9, v146
	v_mov_b32_e32 v10, v146
	v_mov_b32_e32 v11, v146
	v_mov_b32_e32 v12, v146
	v_mov_b32_e32 v13, v146
	v_mov_b32_e32 v14, v146
	v_mov_b32_e32 v15, v146
	v_mov_b32_e32 v16, 0
	v_mov_b32_e32 v17, v146
	v_mov_b32_e32 v18, v146
	v_mov_b32_e32 v19, v146
	v_mov_b32_e32 v20, v146
	v_mov_b32_e32 v21, v146
	v_mov_b32_e32 v22, v146
	v_mov_b32_e32 v23, v146
	v_mov_b32_e32 v24, v146
	v_mov_b32_e32 v25, v146
	v_mov_b32_e32 v26, v146
	v_mov_b32_e32 v27, v146
	v_mov_b32_e32 v28, v146
	v_mov_b32_e32 v29, v146
	v_mov_b32_e32 v30, v146
	v_mov_b32_e32 v31, v146
	v_mov_b32_e32 v32, 0
	v_mov_b32_e32 v33, v146
	v_mov_b32_e32 v34, v146
	v_mov_b32_e32 v35, v146
	v_mov_b32_e32 v36, v146
	v_mov_b32_e32 v37, v146
	v_mov_b32_e32 v42, v146
	v_mov_b32_e32 v43, v146
	v_mov_b32_e32 v44, v146
	v_mov_b32_e32 v45, v146
	v_mov_b32_e32 v46, v146
	v_mov_b32_e32 v47, v146
	v_mov_b32_e32 v48, 0
	v_mov_b32_e32 v49, v146
	v_mov_b32_e32 v50, v146
	v_mov_b32_e32 v51, v146
	s_add_u32 s84, s40, s58
	s_addc_u32 s85, s41, s59
	s_add_u32 s40, s40, s70
	s_addc_u32 s41, s41, s71
